# third deferred-transpose point: workgroups idle in the q/kv-up last round take a slice of the same layer's W2 (25 MB layer 0, 37 MB layer 1) off the in-proj tails
# baseline (speedup 1.0000x reference)
.Ltr_a_m3_end:
	s_load_dwordx2 s[64:65], s[76:77], 0xa8
	s_waitcnt lgkmcnt(0)
	s_mul_i32 s69, s81, 0x4000000
	s_add_u32 s64, s64, s69
	s_addc_u32 s65, s65, 0
	s_mul_i32 s69, s81, 0x5780000
	s_add_u32 s69, s69, 0x3880000
	s_add_u32 s66, s82, s69
	s_addc_u32 s67, s83, 0
	s_mov_b32 s68, 0x4000
	s_mov_b32 s61, 3072
	s_cmp_eq_u32 s81, 1
	s_cmov_b32 s61, 5120
	s_mov_b32 s60, s63
	v_mov_b32_e32 v2, 0x800
	v_mul_u32_u24_e32 v2, v2, v55
	v_add_lshl_u32 v2, v2, v54, 2
	v_mov_b32_e32 v52, 0x4000
	v_mul_u32_u24_e32 v52, v52, v54
	v_lshl_add_u32 v52, v55, 6, v52

.LBB0_477:
	v_readlane_b32 s44, v246, 54
	s_movk_i32 s90, 184
	s_cmp_ge_i32 s44, 11
	s_cmovk_i32 s90, 160
	s_cmp_lt_u32 s2, s90
	s_cbranch_scc1 .Ltr_c_done
	s_lshl_b32 vcc_lo, s3, 10
	s_mov_b32 vcc_hi, m0
	s_mov_b32 m0, vcc_lo
	s_nop 0
	ds_write_addtid_b32 v0 offset:0
	ds_write_addtid_b32 v1 offset:256
	ds_write_addtid_b32 v2 offset:512
	ds_write_addtid_b32 v3 offset:768
	s_waitcnt lgkmcnt(0)
	v_mbcnt_lo_u32_b32 v2, -1, 0
	v_mbcnt_hi_u32_b32 v2, -1, v2
	s_mul_i32 vcc_lo, s3, 13312
	s_add_i32 vcc_lo, vcc_lo, 8192
	v_lshl_add_u32 v0, v2, 4, vcc_lo
	ds_write_b128 v0, v[4:7]
	ds_write_b128 v0, v[8:11] offset:1024
	ds_write_b128 v0, v[12:15] offset:2048
	ds_write_b128 v0, v[16:19] offset:3072
	ds_write_b128 v0, v[20:23] offset:4096
	ds_write_b128 v0, v[24:27] offset:5120
	ds_write_b128 v0, v[28:31] offset:6144
	ds_write_b128 v0, v[32:35] offset:7168
	ds_write_b128 v0, v[36:39] offset:8192
	ds_write_b128 v0, v[40:43] offset:9216
	ds_write_b128 v0, v[44:47] offset:10240
	ds_write_b128 v0, v[48:51] offset:11264
	ds_write_b128 v0, v[52:55] offset:12288
	s_waitcnt lgkmcnt(0)
	v_writelane_b32 v1, s60, 0
	v_writelane_b32 v1, s61, 1
	v_writelane_b32 v1, s62, 2
	v_writelane_b32 v1, s63, 3
	v_writelane_b32 v1, s64, 4
	v_writelane_b32 v1, s65, 5
	v_writelane_b32 v1, s66, 6
	v_writelane_b32 v1, s67, 7
	v_writelane_b32 v1, s68, 8
	v_writelane_b32 v1, s69, 9
	v_writelane_b32 v1, s70, 10
	v_writelane_b32 v1, s71, 11
	v_writelane_b32 v1, s72, 12
	v_writelane_b32 v1, s73, 13
	v_writelane_b32 v1, s74, 14
	v_writelane_b32 v1, s75, 15
	v_writelane_b32 v1, s76, 16
	v_writelane_b32 v1, s77, 17
	v_writelane_b32 v1, s78, 18
	v_writelane_b32 v1, s79, 19
	v_writelane_b32 v1, s80, 20
	v_writelane_b32 v1, s81, 21
	v_writelane_b32 v1, s82, 22
	v_writelane_b32 v1, s83, 23
	v_writelane_b32 v1, vcc_hi, 24
	v_mov_b32_e32 v53, v2
	v_and_b32_e32 v54, 31, v53
	v_lshrrev_b32_e32 v55, 5, v53
	v_readlane_b32 s76, v248, 0
	v_readlane_b32 s77, v248, 1
	s_nop 3
	s_sub_u32 s76, s76, 0xd0
	s_subb_u32 s77, s77, 0
	s_sub_u32 s63, s2, s90
	s_lshl_b32 s63, s63, 3
	s_add_u32 s63, s63, s3
	s_sub_u32 s62, s34, s90
	s_lshl_b32 s62, s62, 3
	s_cmp_ge_i32 s44, 11
	s_cselect_b32 s81, 1, 0
	s_load_dwordx2 s[82:83], s[76:77], 0xc0
	s_load_dwordx2 s[64:65], s[76:77], 0xa8
	s_waitcnt lgkmcnt(0)
	s_mul_i32 s69, s81, 0x4000000
	s_add_u32 s64, s64, s69
	s_addc_u32 s65, s65, 0
	s_mul_i32 s69, s81, 0x5780000
	s_add_u32 s69, s69, 0x3880000
	s_add_u32 s66, s82, s69
	s_addc_u32 s67, s83, 0
	s_mov_b32 s68, 0x4000
	s_mov_b32 s61, 5120
	s_cmp_eq_u32 s81, 1
	s_cmov_b32 s61, 8192
	s_mov_b32 s80, 3072
	s_cmp_eq_u32 s81, 1
	s_cmov_b32 s80, 5120
	s_add_u32 s60, s63, s80
	v_mov_b32_e32 v2, 0x800
	v_mul_u32_u24_e32 v2, v2, v55
	v_add_lshl_u32 v2, v2, v54, 2
	v_mov_b32_e32 v52, 0x4000
	v_mul_u32_u24_e32 v52, v52, v54
	v_lshl_add_u32 v52, v55, 6, v52

.Ltr_c_done:
.LBB0_478:
	v_readlane_b32 s8, v246, 22
	s_add_i32 s14, s44, 4
	v_readlane_b32 s11, v246, 25
	s_cmp_lt_i32 s14, s11
	s_cselect_b64 s[6:7], -1, 0
	s_and_b64 s[0:1], s[4:5], s[6:7]
	s_andn2_b64 vcc, exec, s[0:1]
	v_readlane_b32 s9, v246, 23
	v_readlane_b32 s10, v246, 24
	s_cbranch_vccnz .LBB0_544
	v_readlane_b32 s0, v246, 50
	v_readlane_b32 s1, v246, 51
	s_and_b64 vcc, exec, s[0:1]
	s_cbranch_vccnz .LBB0_491
	s_waitcnt vmcnt(0)
	s_barrier
	s_mov_b64 s[4:5], exec
	v_readlane_b32 s0, v246, 29
	v_readlane_b32 s1, v246, 30
	s_and_b64 s[0:1], s[4:5], s[0:1]
	s_mov_b64 exec, s[0:1]
	s_cbranch_execz .LBB0_490
	v_readlane_b32 s8, v248, 0
	v_readlane_b32 s9, v248, 1
	buffer_wbl2 sc1
	s_load_dwordx2 s[8:9], s[8:9], 0x58
	s_mov_b64 s[0:1], exec
	v_mbcnt_lo_u32_b32 v1, s0, 0
	v_mbcnt_hi_u32_b32 v1, s1, v1
	v_cmp_eq_u32_e32 vcc, 0, v1
	s_waitcnt lgkmcnt(0)
	global_load_dword v0, v161, s[8:9] offset:40
	s_and_saveexec_b64 s[10:11], vcc
	s_cbranch_execz .LBB0_483
	s_bcnt1_i32_b64 s0, s[0:1]
	v_mov_b32_e32 v2, s0
	global_atomic_add v2, v161, v2, s[8:9] offset:32 sc0
